# FFN-up: waves 0-3 issue the epilogue's conv-weight loads before the join barrier
# baseline (speedup 1.0000x reference)
; #define PG8_BAR __builtin_amdgcn_s_barrier()
; __device__ __forceinline__ void epi_ffn(const f32x4 (&acc)[2][2][4][2], const Job& J, int rowt, int pn, int wr, int wc, int fr, int fq, int lane) {
;     ...
;     const int col = 128 * pn + 32 * wc + 8 * fq;
;     f32x4 w0[2], w1[2], w2[2];
; #pragma unroll
;     for (int n = 0; n < 2; ++n) { w0[n] = *(const f32x4*)(cw + col + 4 * n) * (-LOG2E); w1[n] = *(const f32x4*)(cw + DFF + col + 4 * n) * (-LOG2E); w2[n] = *(const f32x4*)(cw + 2 * DFF + col + 4 * n) * (-LOG2E); }
; __device__ __forceinline__ void gemm_phase(LAS unsigned char* lds, const Call& C, const int tid, const Args& args) {
;     ...
;         if (wr == 0) PG8_BAR;
.LBB0_284:
	s_cmp_lg_u32 s55, 4
	s_cbranch_scc1 .Lf1_nb
	s_lshl_b32 s0, s78, 7
	v_readlane_b32 s1, v254, 59
	v_ashrrev_i32_e32 v247, 4, v240
	s_nop 2
	s_or_b32 s0, s0, s1
	s_nop 0
	v_lshl_add_u32 v82, v247, 3, s0
	v_ashrrev_i32_e32 v83, 31, v82
	v_readlane_b32 s0, v254, 17
	v_lshlrev_b64 v[86:87], 2, v[82:83]
	v_readlane_b32 s1, v254, 18
	s_nop 1
	v_lshl_add_u64 v[144:145], s[0:1], 0, v[86:87]
	v_readlane_b32 s0, v255, 21
	v_readlane_b32 s1, v255, 22
	global_load_dwordx4 v[136:139], v[144:145], off
	s_nop 0
	v_lshl_add_u64 v[146:147], s[0:1], 0, v[86:87]
	v_readlane_b32 s0, v255, 23
	v_readlane_b32 s1, v255, 24
	global_load_dwordx4 v[140:143], v[146:147], off
	s_nop 0
	v_lshl_add_u64 v[86:87], s[0:1], 0, v[86:87]
	global_load_dwordx4 v[160:163], v[86:87], off
	global_load_dwordx4 v[164:167], v[144:145], off offset:16
	global_load_dwordx4 v[198:201], v[146:147], off offset:16
	global_load_dwordx4 v[206:209], v[86:87], off offset:16

; __device__ __forceinline__ void epi_ffn(const f32x4 (&acc)[2][2][4][2], const Job& J, int rowt, int pn, int wr, int wc, int fr, int fq, int lane) {
;     bf16_t* O = (bf16_t*)J.out; _Float16* SIDE = (_Float16*)J.out2; const float* cw = J.aux;
;     const int col = 128 * pn + 32 * wc + 8 * fq;
;     f32x4 w0[2], w1[2], w2[2];
; #pragma unroll
;     for (int n = 0; n < 2; ++n) { w0[n] = *(const f32x4*)(cw + col + 4 * n) * (-LOG2E); w1[n] = *(const f32x4*)(cw + DFF + col + 4 * n) * (-LOG2E); w2[n] = *(const f32x4*)(cw + 2 * DFF + col + 4 * n) * (-LOG2E); }
; #pragma unroll
;     for (int ai = 0; ai < 2; ++ai) {
;         const int blk = (rowt + ai * HALF + wr * 64) >> 6;
;         f32x4 cv[4][2];
; #pragma unroll
;         for (int n = 0; n < 2; ++n)
; #pragma unroll
;             for (int e = 0; e < 4; ++e) {
;                 float g[4], dn[4], up[4];
; #pragma unroll
;                 for (int m = 0; m < 4; ++m) { g[m] = acc[ai][0][m][n][e];
;                     dn[m] = __int_as_float(__builtin_amdgcn_mov_dpp(__float_as_int(g[m]), 0x121, 0xF, 0xF, false));
;                     up[m] = __int_as_float(__builtin_amdgcn_mov_dpp(__float_as_int(g[m]), 0x12F, 0xF, 0xF, false)); }
; #pragma unroll
;                 for (int m = 0; m < 4; ++m) {
;                     const float pv = fr > 0 ? dn[m] : (m > 0 ? dn[m - 1] : 0.f);
;                     const float nx = fr < 15 ? up[m] : (m < 3 ? up[m + 1] : 0.f);
;                     cv[m][n][e] = w0[n][e] * pv + w1[n][e] * g[m] + w2[n][e] * nx;
.LBB0_411:
	s_lshl_b32 s0, s78, 7
	v_readlane_b32 s1, v254, 59
	s_or_b32 s0, s0, s1
	v_lshl_add_u32 v82, v247, 3, s0
	v_ashrrev_i32_e32 v83, 31, v82
	v_readlane_b32 s0, v254, 17
	v_lshlrev_b64 v[86:87], 2, v[82:83]
	v_readlane_b32 s1, v254, 18
	v_lshlrev_b64 v[152:153], 1, v[82:83]
	v_mov_b32_dpp v218, v132 row_ror:1 row_mask:0xf bank_mask:0xf
	v_lshl_add_u64 v[144:145], s[0:1], 0, v[86:87]
	v_readlane_b32 s0, v255, 21
	v_readlane_b32 s1, v255, 22
	v_mov_b32_dpp v224, v133 row_ror:1 row_mask:0xf bank_mask:0xf
	v_lshl_add_u64 v[146:147], s[0:1], 0, v[86:87]
	v_readlane_b32 s0, v255, 23
	v_readlane_b32 s1, v255, 24
	v_mov_b32_dpp v192, v134 row_ror:1 row_mask:0xf bank_mask:0xf
	v_lshl_add_u64 v[86:87], s[0:1], 0, v[86:87]
	s_cmp_eq_u64 s[80:81], 0
	s_cbranch_scc0 .Lf1_skipld
	global_load_dwordx4 v[136:139], v[144:145], off
	global_load_dwordx4 v[140:143], v[146:147], off
	global_load_dwordx4 v[160:163], v[86:87], off
	global_load_dwordx4 v[164:167], v[144:145], off offset:16
	global_load_dwordx4 v[198:201], v[146:147], off offset:16
	global_load_dwordx4 v[206:209], v[86:87], off offset:16
.Lf1_skipld:
	s_lshl_b32 s0, s90, 8
	v_readlane_b32 s1, v255, 9
	s_add_i32 s8, s1, s0
	v_readlane_b32 s0, v254, 23
	v_readlane_b32 s1, v254, 24
	v_mov_b32_dpp v211, v135 row_ror:1 row_mask:0xf bank_mask:0xf
	v_mov_b32_dpp v184, v128 row_ror:1 row_mask:0xf bank_mask:0xf
	v_lshl_add_u64 v[82:83], s[0:1], 0, v[152:153]
	s_mov_b32 s0, 0xbfb8aa3b
	v_mov_b32_dpp v194, v129 row_ror:1 row_mask:0xf bank_mask:0xf
	v_cmp_eq_u32_e64 s[40:41], 0, v248
	v_mov_b32_dpp v80, v132 row_ror:15 row_mask:0xf bank_mask:0xf
	v_mov_b32_dpp v217, v124 row_ror:15 row_mask:0xf bank_mask:0xf
	v_mov_b32_dpp v86, v133 row_ror:15 row_mask:0xf bank_mask:0xf
	v_mov_b32_dpp v223, v125 row_ror:15 row_mask:0xf bank_mask:0xf
	v_mov_b32_dpp v87, v134 row_ror:15 row_mask:0xf bank_mask:0xf
	v_mov_b32_dpp v191, v126 row_ror:15 row_mask:0xf bank_mask:0xf
	v_mov_b32_dpp v144, v135 row_ror:15 row_mask:0xf bank_mask:0xf
	v_mov_b32_dpp v210, v127 row_ror:15 row_mask:0xf bank_mask:0xf
	v_mov_b32_dpp v196, v128 row_ror:15 row_mask:0xf bank_mask:0xf
	v_mov_b32_dpp v182, v120 row_ror:15 row_mask:0xf bank_mask:0xf
	v_mov_b32_dpp v216, v129 row_ror:15 row_mask:0xf bank_mask:0xf
	v_cndmask_b32_e64 v203, v224, 0, s[40:41]
	v_cndmask_b32_e64 v202, v218, 0, s[40:41]
	v_cmp_eq_u32_e64 s[42:43], 15, v248
	v_cndmask_b32_e64 v215, v211, 0, s[40:41]
	v_cndmask_b32_e64 v214, v192, 0, s[40:41]
	v_mov_b32_dpp v251, v121 row_ror:15 row_mask:0xf bank_mask:0xf
	v_cndmask_b32_e64 v213, v86, v223, s[42:43]
	v_cndmask_b32_e64 v212, v80, v217, s[42:43]
	v_cndmask_b32_e64 v221, v144, v210, s[42:43]
	v_cndmask_b32_e64 v220, v87, v191, s[42:43]
	v_mov_b32_dpp v222, v130 row_ror:1 row_mask:0xf bank_mask:0xf
	v_mov_b32_dpp v250, v131 row_ror:1 row_mask:0xf bank_mask:0xf
	v_mov_b32_dpp v80, v130 row_ror:15 row_mask:0xf bank_mask:0xf
	v_mov_b32_dpp v249, v123 row_ror:15 row_mask:0xf bank_mask:0xf
	v_cmp_ne_u32_e64 s[44:45], 0, v248
	v_cmp_ne_u32_e64 s[38:39], 15, v248
	v_mov_b32_dpp v193, v124 row_ror:1 row_mask:0xf bank_mask:0xf
	v_mov_b32_dpp v188, v108 row_ror:1 row_mask:0xf bank_mask:0xf
	v_mov_b32_dpp v195, v108 row_ror:15 row_mask:0xf bank_mask:0xf
	v_mov_b32_dpp v190, v92 row_ror:1 row_mask:0xf bank_mask:0xf
	v_mov_b32_dpp v186, v92 row_ror:15 row_mask:0xf bank_mask:0xf
	v_mov_b32_dpp v176, v125 row_ror:1 row_mask:0xf bank_mask:0xf
	v_mov_b32_dpp v179, v109 row_ror:1 row_mask:0xf bank_mask:0xf
	v_mov_b32_dpp v180, v109 row_ror:15 row_mask:0xf bank_mask:0xf
	v_mov_b32_dpp v197, v93 row_ror:1 row_mask:0xf bank_mask:0xf
	v_mov_b32_dpp v183, v93 row_ror:15 row_mask:0xf bank_mask:0xf
	v_mov_b32_dpp v185, v126 row_ror:1 row_mask:0xf bank_mask:0xf
	v_mov_b32_dpp v177, v110 row_ror:1 row_mask:0xf bank_mask:0xf
	v_mov_b32_dpp v187, v110 row_ror:15 row_mask:0xf bank_mask:0xf
	v_mov_b32_dpp v181, v94 row_ror:1 row_mask:0xf bank_mask:0xf
	v_mov_b32_dpp v175, v94 row_ror:15 row_mask:0xf bank_mask:0xf
	v_mov_b32_dpp v172, v127 row_ror:1 row_mask:0xf bank_mask:0xf
	v_mov_b32_dpp v173, v111 row_ror:1 row_mask:0xf bank_mask:0xf
	v_mov_b32_dpp v174, v111 row_ror:15 row_mask:0xf bank_mask:0xf
	v_mov_b32_dpp v189, v95 row_ror:1 row_mask:0xf bank_mask:0xf
	v_mov_b32_dpp v178, v95 row_ror:15 row_mask:0xf bank_mask:0xf
	v_mov_b32_dpp v170, v120 row_ror:1 row_mask:0xf bank_mask:0xf
	v_mov_b32_dpp v168, v104 row_ror:1 row_mask:0xf bank_mask:0xf
	v_mov_b32_dpp v171, v104 row_ror:15 row_mask:0xf bank_mask:0xf
	v_mov_b32_dpp v169, v88 row_ror:1 row_mask:0xf bank_mask:0xf
	v_mov_b32_dpp v85, v88 row_ror:15 row_mask:0xf bank_mask:0xf
	v_mov_b32_dpp v225, v89 row_ror:1 row_mask:0xf bank_mask:0xf
	v_mov_b32_dpp v219, v106 row_ror:15 row_mask:0xf bank_mask:0xf
	s_waitcnt vmcnt(0)
; __device__ __forceinline__ float silu_s(float xs) { return xs * __builtin_amdgcn_rcpf(1.0f + __builtin_amdgcn_exp2f(xs)); }
; __device__ __forceinline__ u32x4 pack8(const f32x4& a, const f32x4& b) { u32x4 w; w.x = cvt_pk_bf16(a[0], a[1]); w.y = cvt_pk_bf16(a[2], a[3]); w.z = cvt_pk_bf16(b[0], b[1]); w.w = cvt_pk_bf16(b[2], b[3]); return w; }
; __device__ __forceinline__ void epi_ffn(const f32x4 (&acc)[2][2][4][2], const Job& J, int rowt, int pn, int wr, int wc, int fr, int fq, int lane) {
;     ...
;                 for (int m = 0; m < 4; ++m) {
;                     const float pv = fr > 0 ? dn[m] : (m > 0 ? dn[m - 1] : 0.f);
;                     const float nx = fr < 15 ? up[m] : (m < 3 ? up[m + 1] : 0.f);
;                     cv[m][n][e] = w0[n][e] * pv + w1[n][e] * g[m] + w2[n][e] * nx;
;                 }
;             }
; #pragma unroll
;         for (int m = 0; m < 4; ++m) {
;             const int grow = rowt + ai * HALF + wr * 64 + m * 16 + fr;
;             const bool first = (m == 0 && fr == 0), last = (m == 3 && fr == 15);
;             if (first || last) {
;                 typedef _Float16 sh4 __attribute__((ext_vector_type(4))); typedef _Float16 sh8 __attribute__((ext_vector_type(8)));
;                 _Float16* sp = SIDE + ((size_t)(blk * 2 + (last ? 1 : 0)) * 3) * DFF + col;
;                 auto pk = [](const f32x4& a, const f32x4& b) { const sh4 x = __builtin_convertvector(a, sh4), y = __builtin_convertvector(b, sh4); return (sh8){x[0], x[1], x[2], x[3], y[0], y[1], y[2], y[3]}; };
;                 *(sh8*)sp = pk(cv[m][0] * NEG_LN2, cv[m][1] * NEG_LN2); *(sh8*)(sp + DFF) = pk(acc[ai][0][m][0], acc[ai][0][m][1]); *(sh8*)(sp + 2 * DFF) = pk(acc[ai][1][m][0], acc[ai][1][m][1]);
;             } else {
;                 f32x4 a0, a1;
; #pragma unroll
;                 for (int e = 0; e < 4; ++e) { a0[e] = silu_s(cv[m][0][e]) * acc[ai][1][m][0][e]; a1[e] = silu_s(cv[m][1][e]) * acc[ai][1][m][1][e]; }
;                 *(u32x4*)(O + (size_t)grow * DFF + col) = pack8(a0, a1);
	v_pk_mul_f32 v[146:147], v[138:139], s[0:1] op_sel_hi:[1,0]
	v_pk_mul_f32 v[154:155], v[136:137], s[0:1] op_sel_hi:[1,0]
	v_pk_mul_f32 v[150:151], v[142:143], s[0:1] op_sel_hi:[1,0]
	v_pk_mul_f32 v[158:159], v[140:141], s[0:1] op_sel_hi:[1,0]
	v_pk_mul_f32 v[142:143], v[198:199], s[0:1] op_sel_hi:[1,0]
	v_pk_mul_f32 v[148:149], v[162:163], s[0:1] op_sel_hi:[1,0]
	v_pk_mul_f32 v[156:157], v[160:161], s[0:1] op_sel_hi:[1,0]
	v_pk_mul_f32 v[140:141], v[164:165], s[0:1] op_sel_hi:[1,0]
	v_pk_mul_f32 v[160:161], v[134:135], v[150:151]
	v_pk_mul_f32 v[162:163], v[132:133], v[158:159]
	v_pk_mul_f32 v[164:165], v[128:129], v[142:143]
	v_cndmask_b32_e64 v199, v194, 0, s[40:41]
	v_cndmask_b32_e64 v198, v184, 0, s[40:41]
	v_pk_mul_f32 v[138:139], v[200:201], s[0:1] op_sel_hi:[1,0]
	v_pk_mul_f32 v[144:145], v[206:207], s[0:1] op_sel_hi:[1,0]
	v_pk_fma_f32 v[162:163], v[154:155], v[202:203], v[162:163]
	v_pk_fma_f32 v[160:161], v[146:147], v[214:215], v[160:161]
	v_cndmask_b32_e64 v201, v216, v251, s[42:43]
	v_cndmask_b32_e64 v200, v196, v182, s[42:43]
	v_pk_fma_f32 v[164:165], v[140:141], v[198:199], v[164:165]
	v_pk_mul_f32 v[136:137], v[166:167], s[0:1] op_sel_hi:[1,0]
	v_pk_fma_f32 v[166:167], v[156:157], v[212:213], v[162:163]
	v_pk_fma_f32 v[162:163], v[148:149], v[220:221], v[160:161]
	v_pk_mul_f32 v[160:161], v[130:131], v[138:139]
	v_pk_fma_f32 v[164:165], v[144:145], v[200:201], v[164:165]
	v_mov_b32_dpp v221, v122 row_ror:15 row_mask:0xf bank_mask:0xf
	v_mov_b32_dpp v202, v131 row_ror:15 row_mask:0xf bank_mask:0xf
	v_cndmask_b32_e64 v201, v250, 0, s[40:41]
	v_cndmask_b32_e64 v200, v222, 0, s[40:41]
	v_pk_mul_f32 v[86:87], v[208:209], s[0:1] op_sel_hi:[1,0]
	v_cndmask_b32_e64 v203, v202, v249, s[42:43]
	v_cndmask_b32_e64 v202, v80, v221, s[42:43]
	v_pk_fma_f32 v[160:161], v[136:137], v[200:201], v[160:161]
	v_mov_b32_dpp v207, v121 row_ror:1 row_mask:0xf bank_mask:0xf
	v_mov_b32_dpp v212, v105 row_ror:1 row_mask:0xf bank_mask:0xf
	v_mov_b32_dpp v213, v105 row_ror:15 row_mask:0xf bank_mask:0xf
	v_mov_b32_dpp v215, v89 row_ror:15 row_mask:0xf bank_mask:0xf
	v_mov_b32_dpp v216, v122 row_ror:1 row_mask:0xf bank_mask:0xf
	v_mov_b32_dpp v208, v106 row_ror:1 row_mask:0xf bank_mask:0xf
	v_mov_b32_dpp v214, v90 row_ror:1 row_mask:0xf bank_mask:0xf
	v_mov_b32_dpp v206, v90 row_ror:15 row_mask:0xf bank_mask:0xf
	v_mov_b32_dpp v196, v123 row_ror:1 row_mask:0xf bank_mask:0xf
	v_mov_b32_dpp v198, v107 row_ror:1 row_mask:0xf bank_mask:0xf
	v_mov_b32_dpp v199, v107 row_ror:15 row_mask:0xf bank_mask:0xf
	v_mov_b32_dpp v220, v91 row_ror:1 row_mask:0xf bank_mask:0xf
	v_mov_b32_dpp v209, v91 row_ror:15 row_mask:0xf bank_mask:0xf
	v_pk_fma_f32 v[160:161], v[86:87], v[202:203], v[160:161]
	v_or_b32_e32 v80, s8, v248
	s_and_saveexec_b64 s[0:1], s[44:45]
	s_xor_b64 s[0:1], exec, s[0:1]
	s_cbranch_execz .LBB0_413
	v_exp_f32_e32 v201, v164
	v_exp_f32_e32 v200, v166
	v_add_f32_e32 v201, 1.0, v201
	v_rcp_f32_e32 v202, v201
	v_exp_f32_e32 v201, v167
	v_add_f32_e32 v200, 1.0, v200
	v_rcp_f32_e32 v200, v200
	v_add_f32_e32 v201, 1.0, v201
	v_rcp_f32_e32 v201, v201
	s_nop 0
	v_pk_mul_f32 v[166:167], v[166:167], v[200:201]
	v_exp_f32_e32 v200, v165
	v_exp_f32_e32 v201, v160
	v_pk_mul_f32 v[166:167], v[116:117], v[166:167]
	v_add_f32_e32 v200, 1.0, v200
	v_rcp_f32_e32 v203, v200
	v_add_f32_e32 v201, 1.0, v201
	v_exp_f32_e32 v200, v162
	v_pk_mul_f32 v[164:165], v[164:165], v[202:203]
	v_rcp_f32_e32 v202, v201
	v_exp_f32_e32 v201, v163
	v_add_f32_e32 v200, 1.0, v200
	v_rcp_f32_e32 v200, v200
	v_pk_mul_f32 v[164:165], v[112:113], v[164:165]
	v_add_f32_e32 v201, 1.0, v201
	v_rcp_f32_e32 v201, v201
	s_nop 0
	v_pk_mul_f32 v[162:163], v[162:163], v[200:201]
	v_exp_f32_e32 v200, v161
	v_pk_mul_f32 v[162:163], v[118:119], v[162:163]
	v_add_f32_e32 v200, 1.0, v200
	v_rcp_f32_e32 v203, v200
	s_nop 0
	v_pk_mul_f32 v[160:161], v[160:161], v[202:203]
	s_nop 0
	v_pk_mul_f32 v[200:201], v[114:115], v[160:161]
	v_cvt_pk_bf16_f32 v160, v166, v167
	v_cvt_pk_bf16_f32 v161, v162, v163
	v_cvt_pk_bf16_f32 v162, v164, v165
	v_cvt_pk_bf16_f32 v163, v200, v201
	v_mad_i64_i32 v[164:165], s[12:13], v80, s46, v[82:83]
	global_store_dwordx4 v[164:165], v[160:163], off sc1
